# v3 + attention main loop: row-max tree without canonicalising copies, slot SALU moved into the MFMA->VALU pad
# baseline (speedup 1.0000x reference)
.LBB0_832:
	v_cvt_pk_bf16_f32 v172, v104, v105
	v_cvt_pk_bf16_f32 v180, v96, v97
	s_add_i32 s12, s67, -3
	s_and_b32 s22, s12, 3
	s_mulk_i32 s22, 0x3000
	v_add_u32_e32 v0, s22, v214
	ds_read_b128 v[2:5], v0 offset:4096
	v_add_u32_e32 v14, s62, v217
	s_waitcnt lgkmcnt(4)
	v_mfma_f32_32x32x16_bf16 v[128:143], v[196:199], v[176:179], v[64:79]
	v_add_f32_e32 v6, v96, v97
	v_add_f32_e32 v6, v98, v6
	v_add_f32_e32 v6, v99, v6
	v_add_f32_e32 v10, v100, v6
	ds_read_b128 v[6:9], v0 offset:4608
	s_waitcnt lgkmcnt(4)
	v_mfma_f32_32x32x16_bf16 v[112:127], v[184:187], v[176:179], v[64:79]
	v_add_f32_e32 v10, v101, v10
	v_add_f32_e32 v10, v102, v10
	v_add_f32_e32 v15, v103, v10
	v_cvt_pk_bf16_f32 v181, v98, v99
	ds_read_b128 v[10:13], v0 offset:6144
	s_waitcnt lgkmcnt(4)
	v_mfma_f32_32x32x16_bf16 v[128:143], v[188:191], v[168:171], v[128:143]
	v_add_f32_e32 v15, v104, v15
	v_add_f32_e32 v15, v105, v15
	v_add_f32_e32 v15, v106, v15
	v_cvt_pk_bf16_f32 v182, v100, v101
	ds_read_b128 v[96:99], v0 offset:6656
	s_waitcnt lgkmcnt(4)
	v_mfma_f32_32x32x16_bf16 v[112:127], v[192:195], v[168:171], v[112:127]
	v_add_f32_e32 v15, v107, v15
	v_add_f32_e32 v15, v108, v15
	v_add_f32_e32 v15, v109, v15
	v_cvt_pk_bf16_f32 v183, v102, v103
	ds_read_b128 v[100:103], v0 offset:8192
	s_waitcnt lgkmcnt(4)
	v_mfma_f32_32x32x16_bf16 v[128:143], v[2:5], v[164:167], v[128:143]
	v_add_f32_e32 v15, v110, v15
	v_add_f32_e32 v15, v111, v15
	v_add_f32_e32 v15, v80, v15
	ds_read_b128 v[2:5], v0 offset:8704
	s_waitcnt lgkmcnt(4)
	v_mfma_f32_32x32x16_bf16 v[112:127], v[6:9], v[164:167], v[112:127]
	v_add_f32_e32 v15, v81, v15
	v_add_f32_e32 v15, v82, v15
	v_add_f32_e32 v15, v83, v15
	v_cvt_pk_bf16_f32 v173, v106, v107
	ds_read_b128 v[104:107], v0 offset:10240
	s_waitcnt lgkmcnt(4)
	v_mfma_f32_32x32x16_bf16 v[128:143], v[10:13], v[156:159], v[128:143]
	v_add_f32_e32 v6, v84, v15
	v_add_f32_e32 v6, v85, v6
	v_cvt_pk_bf16_f32 v174, v108, v109
	v_cvt_pk_bf16_f32 v175, v110, v111
	ds_read_b128 v[108:111], v0 offset:10752
	s_waitcnt lgkmcnt(4)
	v_mfma_f32_32x32x16_bf16 v[112:127], v[96:99], v[156:159], v[112:127]
	v_add_f32_e32 v0, v86, v6
	v_add_f32_e32 v0, v87, v0
	v_cvt_pk_bf16_f32 v160, v80, v81
	v_cvt_pk_bf16_f32 v161, v82, v83
	s_add_u32 s62, s58, 0xffff0000
	s_addc_u32 s63, s59, -1
	s_and_b32 s12, s67, 3
	s_mulk_i32 s12, 0x3000
	s_add_i32 s64, s12, s78
	s_mov_b32 m0, s64
	s_nop 0
	global_load_lds_dwordx4 v216, s[62:63]
	ds_read_b64_tr_b16 v[6:7], v14 offset:49152
	ds_read_b64_tr_b16 v[8:9], v14 offset:49664
	s_waitcnt lgkmcnt(5)
	v_mfma_f32_32x32x16_bf16 v[128:143], v[100:103], v[148:151], v[128:143]
	v_add_f32_e32 v0, v88, v0
	v_add_f32_e32 v0, v89, v0
	v_cvt_pk_bf16_f32 v162, v84, v85
	v_cvt_pk_bf16_f32 v163, v86, v87
	s_add_u32 s62, s60, 0xfffff000
	s_addc_u32 s63, s61, -1
	s_add_i32 s12, s12, s85
	s_mov_b32 m0, s12
	s_nop 0
	global_load_lds_dwordx4 v216, s[62:63]
	ds_read_b64_tr_b16 v[10:11], v14 offset:53248
	ds_read_b64_tr_b16 v[12:13], v14 offset:53760
	s_waitcnt lgkmcnt(6)
	v_mfma_f32_32x32x16_bf16 v[112:127], v[2:5], v[148:151], v[112:127]
	v_add_f32_e32 v0, v90, v0
	v_add_f32_e32 v0, v91, v0
	v_cvt_pk_bf16_f32 v152, v88, v89
	v_cvt_pk_bf16_f32 v153, v90, v91
	s_add_u32 s62, s6, 0xffff0000
	s_addc_u32 s63, s7, -1
	s_add_i32 s12, s23, s86
	s_mov_b32 m0, s12
	s_nop 0
	global_load_lds_dwordx4 v216, s[62:63]
	ds_read_b64_tr_b16 v[80:81], v14 offset:50176
	ds_read_b64_tr_b16 v[82:83], v14 offset:50688
	s_waitcnt lgkmcnt(7)
	v_mfma_f32_32x32x16_bf16 v[128:143], v[104:107], v[144:147], v[128:143]
	v_add_f32_e32 v0, v92, v0
	v_add_f32_e32 v0, v93, v0
	v_cvt_pk_bf16_f32 v154, v92, v93
	ds_read_b64_tr_b16 v[2:3], v14 offset:54272
	ds_read_b64_tr_b16 v[4:5], v14 offset:54784
	s_waitcnt lgkmcnt(8)
	v_mfma_f32_32x32x16_bf16 v[112:127], v[108:111], v[144:147], v[112:127]
	v_add_f32_e32 v0, v94, v0
	v_add_f32_e32 v0, v95, v0
	v_cvt_pk_bf16_f32 v155, v94, v95
	s_nop 1
	v_max_f32_e32 v15, v128, v129
	s_add_i32 s12, s67, -2
	s_and_b32 s12, s12, 3
	s_mulk_i32 s12, 0x3000
	s_nop 2
	v_max3_f32 v84, v130, v131, v113
	v_max3_f32 v15, v15, v112, v114
	v_max3_f32 v15, v15, v115, v132
	v_max3_f32 v84, v84, v134, v135
	v_max3_f32 v15, v15, v133, v116
	v_max3_f32 v84, v84, v118, v119
	v_max3_f32 v15, v15, v117, v136
	v_max3_f32 v84, v84, v138, v139
	v_max3_f32 v15, v15, v137, v120
	v_max3_f32 v84, v84, v122, v123
	v_max3_f32 v15, v15, v121, v140
	v_max3_f32 v84, v84, v142, v143
	v_max3_f32 v15, v15, v141, v124
	v_max3_f32 v84, v84, v126, v127
	v_max3_f32 v15, v15, v125, v84
	v_mov_b32_e32 v84, v15
	s_nop 1
	v_permlane32_swap_b32_e32 v15, v84
	v_max_f32_e32 v15, v15, v84
	v_cmp_lt_f32_e32 vcc, s94, v15
	s_cmp_lg_u64 vcc, 0
	v_add_f32_e32 v0, v218, v0
	s_cselect_b64 s[62:63], -1, 0
	s_cbranch_vccnz .LBB0_840
.LBB0_833:
	s_waitcnt lgkmcnt(6)
	v_mfma_f32_32x32x16_bf16 v[48:63], v[180:183], v[6:9], v[48:63]
	v_exp_f32_e32 v128, v128
	v_exp_f32_e32 v129, v129
	v_exp_f32_e32 v130, v130
	v_exp_f32_e32 v131, v131
	ds_read_b64_tr_b16 v[6:7], v14 offset:51200
	ds_read_b64_tr_b16 v[8:9], v14 offset:51712
	s_waitcnt lgkmcnt(6)
	v_mfma_f32_32x32x16_bf16 v[32:47], v[180:183], v[10:13], v[32:47]
	v_exp_f32_e32 v132, v132
	v_exp_f32_e32 v133, v133
	v_exp_f32_e32 v134, v134
	v_exp_f32_e32 v135, v135
	ds_read_b64_tr_b16 v[10:11], v14 offset:55296
	ds_read_b64_tr_b16 v[12:13], v14 offset:55808
	s_waitcnt lgkmcnt(6)
	v_mfma_f32_32x32x16_bf16 v[48:63], v[172:175], v[80:83], v[48:63]
	v_exp_f32_e32 v136, v136
	v_exp_f32_e32 v137, v137
	v_exp_f32_e32 v138, v138
	v_exp_f32_e32 v139, v139
	ds_read_b64_tr_b16 v[80:81], v14 offset:52224
	ds_read_b64_tr_b16 v[82:83], v14 offset:52736
	s_waitcnt lgkmcnt(6)
	v_mfma_f32_32x32x16_bf16 v[32:47], v[172:175], v[2:5], v[32:47]
	v_exp_f32_e32 v140, v140
	v_exp_f32_e32 v141, v141
	v_exp_f32_e32 v142, v142
	v_exp_f32_e32 v143, v143
	v_add_u32_e32 v15, s12, v214
	ds_read_b64_tr_b16 v[84:85], v14 offset:56320
	ds_read_b64_tr_b16 v[86:87], v14 offset:56832
	ds_read_b128 v[2:5], v15
	s_waitcnt lgkmcnt(7)
	v_mfma_f32_32x32x16_bf16 v[48:63], v[160:163], v[6:9], v[48:63]
	v_exp_f32_e32 v112, v112
	v_exp_f32_e32 v113, v113
	v_exp_f32_e32 v114, v114
	v_exp_f32_e32 v115, v115
	ds_read_b128 v[6:9], v15 offset:512
	s_waitcnt lgkmcnt(6)
	v_mfma_f32_32x32x16_bf16 v[32:47], v[160:163], v[10:13], v[32:47]
	v_exp_f32_e32 v116, v116
	v_exp_f32_e32 v117, v117
	v_exp_f32_e32 v118, v118
	v_exp_f32_e32 v119, v119
	ds_read_b128 v[10:13], v15 offset:2048
	s_waitcnt lgkmcnt(5)
	v_mfma_f32_32x32x16_bf16 v[48:63], v[152:155], v[80:83], v[48:63]
	v_exp_f32_e32 v120, v120
	v_exp_f32_e32 v121, v121
	v_exp_f32_e32 v122, v122
	v_exp_f32_e32 v123, v123
	ds_read_b128 v[184:187], v15 offset:2560
	s_waitcnt lgkmcnt(4)
	v_mfma_f32_32x32x16_bf16 v[32:47], v[152:155], v[84:87], v[32:47]
	v_exp_f32_e32 v124, v124
	v_exp_f32_e32 v125, v125
	v_exp_f32_e32 v126, v126
	v_exp_f32_e32 v127, v127
	s_waitcnt vmcnt(3) lgkmcnt(0)
	s_barrier
	s_andn2_b64 vcc, exec, s[62:63]
	s_cbranch_vccnz .LBB0_835
	s_waitcnt lgkmcnt(0)
	ds_read_b128 v[80:83], v207 offset:96
	ds_read_b128 v[84:87], v207 offset:64
	ds_read_b128 v[88:91], v207 offset:32
	ds_read_b128 v[92:95], v207
	s_waitcnt lgkmcnt(3)
	v_pk_mul_f32 v[62:63], v[62:63], v[82:83]
	s_waitcnt lgkmcnt(2)
	v_pk_mul_f32 v[58:59], v[58:59], v[86:87]
	s_waitcnt lgkmcnt(1)
	v_pk_mul_f32 v[54:55], v[54:55], v[90:91]
	s_waitcnt lgkmcnt(0)
	v_pk_mul_f32 v[50:51], v[50:51], v[94:95]
	v_pk_mul_f32 v[60:61], v[60:61], v[80:81]
	v_pk_mul_f32 v[56:57], v[56:57], v[84:85]
	v_pk_mul_f32 v[52:53], v[52:53], v[88:89]
	v_pk_mul_f32 v[48:49], v[48:49], v[92:93]
	v_pk_mul_f32 v[46:47], v[46:47], v[82:83]
	v_pk_mul_f32 v[42:43], v[42:43], v[86:87]
	v_pk_mul_f32 v[38:39], v[38:39], v[90:91]
	v_pk_mul_f32 v[34:35], v[34:35], v[94:95]
	v_pk_mul_f32 v[44:45], v[44:45], v[80:81]
	v_pk_mul_f32 v[40:41], v[40:41], v[84:85]
	v_pk_mul_f32 v[36:37], v[36:37], v[88:89]
	v_pk_mul_f32 v[32:33], v[32:33], v[92:93]
.LBB0_835:
	s_add_i32 s12, s23, 0x2000
	s_cmpk_lg_i32 s23, 0x4000
	s_cselect_b32 s12, s12, 0
	ds_read_b128 v[188:191], v15 offset:4096
	v_add_u32_e32 v14, s10, v217
	s_waitcnt lgkmcnt(4)
	v_mfma_f32_32x32x16_bf16 v[96:111], v[2:5], v[176:179], v[64:79]
	v_add_f32_e32 v80, v128, v129
	v_add_f32_e32 v80, v130, v80
	v_add_f32_e32 v80, v131, v80
	v_add_f32_e32 v80, v132, v80
	v_cvt_pk_bf16_f32 v180, v128, v129
	ds_read_b128 v[2:5], v15 offset:4608
	v_add_f32_e32 v80, v133, v80
	v_add_f32_e32 v80, v134, v80
	v_add_f32_e32 v128, v135, v80
	s_waitcnt lgkmcnt(4)
	v_mfma_f32_32x32x16_bf16 v[80:95], v[6:9], v[176:179], v[64:79]
	v_cvt_pk_bf16_f32 v181, v130, v131
	ds_read_b128 v[6:9], v15 offset:6144
	s_waitcnt lgkmcnt(4)
	v_mfma_f32_32x32x16_bf16 v[96:111], v[10:13], v[168:171], v[96:111]
	v_add_f32_e32 v128, v136, v128
	v_add_f32_e32 v128, v137, v128
	v_add_f32_e32 v128, v138, v128
	v_cvt_pk_bf16_f32 v182, v132, v133
	ds_read_b128 v[10:13], v15 offset:6656
	s_waitcnt lgkmcnt(4)
	v_mfma_f32_32x32x16_bf16 v[80:95], v[184:187], v[168:171], v[80:95]
	v_add_f32_e32 v128, v139, v128
	v_add_f32_e32 v128, v140, v128
	v_add_f32_e32 v132, v141, v128
	v_cvt_pk_bf16_f32 v183, v134, v135
	ds_read_b128 v[128:131], v15 offset:8192
	s_waitcnt lgkmcnt(4)
	v_mfma_f32_32x32x16_bf16 v[96:111], v[188:191], v[164:167], v[96:111]
	v_add_f32_e32 v132, v142, v132
	v_add_f32_e32 v132, v143, v132
	v_add_f32_e32 v152, v112, v132
	v_cvt_pk_bf16_f32 v172, v136, v137
	ds_read_b128 v[132:135], v15 offset:8704
	s_waitcnt lgkmcnt(4)
	v_mfma_f32_32x32x16_bf16 v[80:95], v[2:5], v[164:167], v[80:95]
	v_add_f32_e32 v136, v113, v152
	v_add_f32_e32 v136, v114, v136
	v_add_f32_e32 v136, v115, v136
	v_cvt_pk_bf16_f32 v173, v138, v139
	ds_read_b128 v[2:5], v15 offset:10240
	s_waitcnt lgkmcnt(4)
	v_mfma_f32_32x32x16_bf16 v[96:111], v[6:9], v[156:159], v[96:111]
	v_add_f32_e32 v136, v116, v136
	v_add_f32_e32 v152, v117, v136
	v_cvt_pk_bf16_f32 v174, v140, v141
	v_cvt_pk_bf16_f32 v175, v142, v143
	ds_read_b128 v[136:139], v15 offset:10752
	s_waitcnt lgkmcnt(4)
	v_mfma_f32_32x32x16_bf16 v[80:95], v[10:13], v[156:159], v[80:95]
	v_add_f32_e32 v6, v118, v152
	v_add_f32_e32 v6, v119, v6
	v_cvt_pk_bf16_f32 v160, v112, v113
	v_cvt_pk_bf16_f32 v161, v114, v115
	s_add_i32 s10, s22, s78
	s_mov_b32 m0, s10
	s_nop 0
	global_load_lds_dwordx4 v216, s[58:59]
	ds_read_b64_tr_b16 v[112:113], v14 offset:49152
	ds_read_b64_tr_b16 v[114:115], v14 offset:49664
	s_waitcnt lgkmcnt(5)
	v_mfma_f32_32x32x16_bf16 v[96:111], v[128:131], v[148:151], v[96:111]
	v_add_f32_e32 v6, v120, v6
	v_add_f32_e32 v6, v121, v6
	v_cvt_pk_bf16_f32 v162, v116, v117
	v_cvt_pk_bf16_f32 v163, v118, v119
	s_add_i32 s10, s22, s85
	s_mov_b32 m0, s10
	s_nop 0
	global_load_lds_dwordx4 v216, s[60:61]
	ds_read_b64_tr_b16 v[10:11], v14 offset:53248
	ds_read_b64_tr_b16 v[12:13], v14 offset:53760
	s_waitcnt lgkmcnt(6)
	v_mfma_f32_32x32x16_bf16 v[80:95], v[132:135], v[148:151], v[80:95]
	v_add_f32_e32 v6, v122, v6
	v_add_f32_e32 v15, v123, v6
	v_cvt_pk_bf16_f32 v152, v120, v121
	v_cvt_pk_bf16_f32 v153, v122, v123
	s_add_i32 s10, s12, s86
	s_mov_b32 m0, s10
	s_nop 0
	global_load_lds_dwordx4 v216, s[6:7]
	ds_read_b64_tr_b16 v[6:7], v14 offset:50176
	ds_read_b64_tr_b16 v[8:9], v14 offset:50688
	s_waitcnt lgkmcnt(7)
	v_mfma_f32_32x32x16_bf16 v[96:111], v[2:5], v[144:147], v[96:111]
	v_add_f32_e32 v15, v124, v15
	v_add_f32_e32 v15, v125, v15
	v_cvt_pk_bf16_f32 v154, v124, v125
	ds_read_b64_tr_b16 v[2:3], v14 offset:54272
	ds_read_b64_tr_b16 v[4:5], v14 offset:54784
	s_waitcnt lgkmcnt(8)
	v_mfma_f32_32x32x16_bf16 v[80:95], v[136:139], v[144:147], v[80:95]
	v_add_f32_e32 v15, v126, v15
	v_add_f32_e32 v15, v127, v15
	v_cvt_pk_bf16_f32 v155, v126, v127
	s_nop 1
	v_max_f32_e32 v116, v96, v97
	s_add_i32 s10, s67, -1
	s_and_b32 s22, s10, 3
	s_mulk_i32 s22, 0x3000
	s_nop 2
	v_max3_f32 v117, v98, v99, v81
	v_max3_f32 v116, v116, v80, v82
	v_max3_f32 v116, v116, v83, v100
	v_max3_f32 v117, v117, v102, v103
	v_max3_f32 v116, v116, v101, v84
	v_max3_f32 v117, v117, v86, v87
	v_max3_f32 v116, v116, v85, v104
	v_max3_f32 v117, v117, v106, v107
	v_max3_f32 v116, v116, v105, v88
	v_max3_f32 v117, v117, v90, v91
	v_max3_f32 v116, v116, v89, v108
	v_max3_f32 v117, v117, v110, v111
	v_max3_f32 v116, v116, v109, v92
	v_max3_f32 v117, v117, v94, v95
	v_add_f32_e32 v218, v0, v15
	v_max3_f32 v0, v116, v93, v117
	v_mov_b32_e32 v15, v0
	s_nop 1
	v_permlane32_swap_b32_e32 v0, v15
	v_max_f32_e32 v0, v0, v15
	v_cmp_lt_f32_e32 vcc, s94, v0
	s_cmp_lg_u64 vcc, 0
	s_cselect_b64 s[62:63], -1, 0
	s_cbranch_vccnz .LBB0_843
.LBB0_836:
	s_waitcnt lgkmcnt(6)
	v_mfma_f32_32x32x16_bf16 v[48:63], v[180:183], v[112:115], v[48:63]
	v_exp_f32_e32 v96, v96
	v_exp_f32_e32 v97, v97
	v_exp_f32_e32 v98, v98
	v_exp_f32_e32 v99, v99
	ds_read_b64_tr_b16 v[112:113], v14 offset:51200
	ds_read_b64_tr_b16 v[114:115], v14 offset:51712
	s_waitcnt lgkmcnt(6)
	v_mfma_f32_32x32x16_bf16 v[32:47], v[180:183], v[10:13], v[32:47]
	v_exp_f32_e32 v100, v100
	v_exp_f32_e32 v101, v101
	v_exp_f32_e32 v102, v102
	v_exp_f32_e32 v103, v103
	ds_read_b64_tr_b16 v[10:11], v14 offset:55296
	ds_read_b64_tr_b16 v[12:13], v14 offset:55808
	s_waitcnt lgkmcnt(6)
	v_mfma_f32_32x32x16_bf16 v[48:63], v[172:175], v[6:9], v[48:63]
	v_exp_f32_e32 v104, v104
	v_exp_f32_e32 v105, v105
	v_exp_f32_e32 v106, v106
	v_exp_f32_e32 v107, v107
	ds_read_b64_tr_b16 v[6:7], v14 offset:52224
	ds_read_b64_tr_b16 v[8:9], v14 offset:52736
	s_waitcnt lgkmcnt(6)
	v_mfma_f32_32x32x16_bf16 v[32:47], v[172:175], v[2:5], v[32:47]
	v_exp_f32_e32 v108, v108
	v_exp_f32_e32 v109, v109
	v_exp_f32_e32 v110, v110
	v_exp_f32_e32 v111, v111
	v_add_u32_e32 v0, s22, v214
	ds_read_b64_tr_b16 v[2:3], v14 offset:56320
	ds_read_b64_tr_b16 v[4:5], v14 offset:56832
	ds_read_b128 v[196:199], v0
	s_waitcnt lgkmcnt(7)
	v_mfma_f32_32x32x16_bf16 v[48:63], v[160:163], v[112:115], v[48:63]
	v_exp_f32_e32 v80, v80
	v_exp_f32_e32 v81, v81
	v_exp_f32_e32 v82, v82
	v_exp_f32_e32 v83, v83
	ds_read_b128 v[184:187], v0 offset:512
	s_waitcnt lgkmcnt(6)
	v_mfma_f32_32x32x16_bf16 v[32:47], v[160:163], v[10:13], v[32:47]
	v_exp_f32_e32 v84, v84
	v_exp_f32_e32 v85, v85
	v_exp_f32_e32 v86, v86
	v_exp_f32_e32 v87, v87
	ds_read_b128 v[188:191], v0 offset:2048
	s_waitcnt lgkmcnt(5)
	v_mfma_f32_32x32x16_bf16 v[48:63], v[152:155], v[6:9], v[48:63]
	v_exp_f32_e32 v88, v88
	v_exp_f32_e32 v89, v89
	v_exp_f32_e32 v90, v90
	v_exp_f32_e32 v91, v91
	ds_read_b128 v[192:195], v0 offset:2560
	s_waitcnt lgkmcnt(4)
	v_mfma_f32_32x32x16_bf16 v[32:47], v[152:155], v[2:5], v[32:47]
	v_exp_f32_e32 v92, v92
	v_exp_f32_e32 v93, v93
	v_exp_f32_e32 v94, v94
	v_exp_f32_e32 v95, v95
	s_waitcnt vmcnt(3) lgkmcnt(0)
	s_barrier
	s_andn2_b64 vcc, exec, s[62:63]
	s_cbranch_vccnz .LBB0_838
	s_waitcnt lgkmcnt(0)
	ds_read_b128 v[2:5], v207 offset:96
	ds_read_b128 v[6:9], v207 offset:64
	ds_read_b128 v[10:13], v207 offset:32
	ds_read_b128 v[112:115], v207
	s_waitcnt lgkmcnt(3)
	v_pk_mul_f32 v[62:63], v[62:63], v[4:5]
	s_waitcnt lgkmcnt(2)
	v_pk_mul_f32 v[58:59], v[58:59], v[8:9]
	s_waitcnt lgkmcnt(1)
	v_pk_mul_f32 v[54:55], v[54:55], v[12:13]
	s_waitcnt lgkmcnt(0)
	v_pk_mul_f32 v[50:51], v[50:51], v[114:115]
	v_pk_mul_f32 v[60:61], v[60:61], v[2:3]
	v_pk_mul_f32 v[56:57], v[56:57], v[6:7]
	v_pk_mul_f32 v[52:53], v[52:53], v[10:11]
	v_pk_mul_f32 v[48:49], v[48:49], v[112:113]
	v_pk_mul_f32 v[46:47], v[46:47], v[4:5]
	v_pk_mul_f32 v[42:43], v[42:43], v[8:9]
	v_pk_mul_f32 v[38:39], v[38:39], v[12:13]
	v_pk_mul_f32 v[34:35], v[34:35], v[114:115]
	v_pk_mul_f32 v[44:45], v[44:45], v[2:3]
	v_pk_mul_f32 v[40:41], v[40:41], v[6:7]
	v_pk_mul_f32 v[36:37], v[36:37], v[10:11]
	v_pk_mul_f32 v[32:33], v[32:33], v[112:113]
